# nt cache policy on the once-read f32 activation row loads of the prologue rmsnorm
# speedup vs baseline: 1.0574x; 1.0088x over previous
.LBB0_22:
	s_add_u32 s36, s22, 0x9800000
	s_mov_b32 s8, 0
	s_addc_u32 s37, s23, 0
	s_ashr_i32 s9, s8, 31
	s_lshl_b64 s[8:9], s[8:9], 3
	s_add_u32 s8, s0, s8
	s_addc_u32 s9, s1, s9
	s_mov_b32 s10, 1
	s_load_dwordx2 s[8:9], s[8:9], 0x0
	s_ashr_i32 s11, s10, 31
	s_lshl_b64 s[10:11], s[10:11], 3
	s_add_u32 s10, s0, s10
	s_addc_u32 s11, s1, s11
	s_mov_b32 s12, 5
	s_load_dwordx2 s[10:11], s[10:11], 0x0
	s_ashr_i32 s13, s12, 31
	s_lshl_b64 s[12:13], s[12:13], 3
	s_add_u32 s12, s0, s12
	s_addc_u32 s13, s1, s13
	s_load_dwordx2 s[14:15], s[12:13], 0x0
	s_ashr_i32 s5, s4, 31
	s_lshl_b64 s[4:5], s[4:5], 3
	s_add_u32 s4, s0, s4
	s_addc_u32 s5, s1, s5
	s_load_dwordx2 s[34:35], s[4:5], 0x0
	s_mov_b32 s4, 17
	s_ashr_i32 s5, s4, 31
	s_lshl_b64 s[4:5], s[4:5], 3
	s_add_u32 s4, s0, s4
	s_addc_u32 s5, s1, s5
	s_mul_i32 s3, s26, 24
	s_load_dwordx2 s[38:39], s[4:5], 0x0
	s_add_i32 s12, s24, s3
	s_mov_b32 s4, s12
	v_writelane_b32 v226, s4, 1
	s_cmpk_lt_i32 s12, 0x2000
	v_mbcnt_lo_u32_b32 v165, -1, 0
	v_writelane_b32 v226, s5, 2
	s_cselect_b64 s[4:5], -1, 0
	v_writelane_b32 v226, s4, 3
	s_and_b64 vcc, exec, s[4:5]
	v_lshlrev_b32_e32 v126, 3, v128
	s_mov_b32 s40, s24
	v_writelane_b32 v226, s5, 4
	s_cbranch_vccz .LBB0_24
	s_ashr_i32 s25, s24, 31
	s_lshl_b64 s[4:5], s[24:25], 13
	s_waitcnt lgkmcnt(0)
	s_add_u32 s4, s8, s4
	v_lshlrev_b32_e32 v130, 4, v128
	s_addc_u32 s5, s9, s5
	v_or_b32_e32 v1, 0x1400, v130
	global_load_dwordx4 v[18:21], v130, s[4:5] nt
	global_load_dwordx4 v[74:77], v130, s[4:5] offset:1024 nt
	global_load_dwordx4 v[14:17], v130, s[4:5] offset:2048 nt
	global_load_dwordx4 v[2:5], v1, s[4:5] nt
	v_or_b32_e32 v34, 0x1000, v130
	global_load_dwordx4 v[6:9], v34, s[4:5] nt
	global_load_dwordx4 v[10:13], v130, s[4:5] offset:3072 nt
	v_or_b32_e32 v35, 0x1800, v130
	v_or_b32_e32 v78, 0x1c00, v130
	global_load_dwordx4 v[118:121], v35, s[4:5] nt
	global_load_dwordx4 v[110:113], v78, s[4:5] nt
	s_lshl_b32 s3, s26, 4
	v_readlane_b32 s28, v226, 1
	s_sub_i32 s42, s28, s3
	s_ashr_i32 s43, s42, 31
	s_lshl_b64 s[4:5], s[42:43], 13
	s_add_u32 s4, s8, s4
	s_addc_u32 s5, s9, s5
	global_load_dwordx4 v[102:105], v130, s[4:5] nt
	global_load_dwordx4 v[114:117], v130, s[4:5] offset:1024 nt
	global_load_dwordx4 v[106:109], v130, s[4:5] offset:2048 nt
	v_add_u32_e32 v204, 0x1000, v130
	global_load_dwordx4 v[166:169], v130, s[34:35]
	global_load_dwordx4 v[170:173], v130, s[34:35] offset:1024
	global_load_dwordx4 v[174:177], v130, s[34:35] offset:2048
	global_load_dwordx4 v[178:181], v130, s[34:35] offset:3072
	global_load_dwordx4 v[182:185], v204, s[34:35]
	global_load_dwordx4 v[186:189], v204, s[34:35] offset:1024
	global_load_dwordx4 v[190:193], v204, s[34:35] offset:2048
	global_load_dwordx4 v[200:203], v204, s[34:35] offset:3072
	global_load_dwordx4 v[94:97], v1, s[4:5] nt
	global_load_dwordx4 v[98:101], v34, s[4:5] nt
	global_load_dwordx4 v[90:93], v35, s[4:5] nt
	global_load_dwordx4 v[62:65], v78, s[4:5] nt
	global_load_dwordx4 v[122:125], v130, s[4:5] offset:3072 nt
	s_add_i32 s4, s42, s18
	s_ashr_i32 s5, s4, 31
	s_lshl_b64 s[40:41], s[4:5], 13
	s_mov_b32 s46, 0x358637bd
	s_add_u32 s44, s8, s40
	s_mov_b32 s40, 0x3a000000
	v_mov_b64_e32 v[132:133], s[46:47]
	s_mov_b32 s3, 0x800000
	v_readlane_b32 s29, v226, 2
	s_addc_u32 s45, s9, s41
	s_ashr_i32 s29, s28, 31
	s_lshl_b64 s[46:47], s[28:29], 13
	s_add_u32 s46, s8, s46
	s_addc_u32 s47, s9, s47
	v_mov_b32_e32 v131, 0
	s_movk_i32 s12, 0x1000
	s_waitcnt vmcnt(23)
	v_mov_b32_e32 v28, v19
	s_waitcnt vmcnt(22)
	v_mov_b32_e32 v29, v75
	s_waitcnt vmcnt(21)
	v_pk_mul_f32 v[30:31], v[16:17], v[16:17]
	v_pk_mul_f32 v[32:33], v[14:15], v[14:15]
	s_waitcnt vmcnt(20)
	v_pk_mul_f32 v[36:37], v[4:5], v[4:5]
	v_pk_mul_f32 v[38:39], v[2:3], v[2:3]
	v_mov_b32_e32 v42, v21
	v_mov_b32_e32 v43, v77
	v_mov_b32_e32 v26, v18
	v_mov_b32_e32 v27, v74
	v_mov_b32_e32 v40, v20
	v_mov_b32_e32 v41, v76
	v_pk_mov_b32 v[52:53], v[32:33], v[30:31] op_sel:[1,0]
	v_mov_b32_e32 v33, v31
	v_pk_mov_b32 v[30:31], v[38:39], v[36:37] op_sel:[1,0]
	v_mov_b32_e32 v39, v37
	v_pk_mul_f32 v[28:29], v[28:29], v[28:29]
	v_pk_mul_f32 v[36:37], v[42:43], v[42:43]
	v_pk_fma_f32 v[26:27], v[26:27], v[26:27], v[28:29]
	v_pk_fma_f32 v[28:29], v[40:41], v[40:41], v[36:37]
	s_waitcnt vmcnt(18)
	v_mul_f32_e32 v44, v11, v11
	v_mul_f32_e32 v46, v13, v13
	v_pk_add_f32 v[32:33], v[52:53], v[32:33]
	v_pk_add_f32 v[26:27], v[26:27], v[28:29]
	v_mul_f32_e32 v51, v8, v8
	v_mul_f32_e32 v54, v9, v9
	v_mul_f32_e32 v57, v7, v7
	v_mul_f32_e32 v58, v6, v6
	v_pk_fma_f32 v[42:43], v[10:11], v[10:11], v[44:45] op_sel_hi:[1,1,0]
	v_pk_fma_f32 v[44:45], v[12:13], v[12:13], v[46:47] op_sel_hi:[1,1,0]
	v_pk_add_f32 v[32:33], v[32:33], v[32:33] op_sel:[0,1] op_sel_hi:[1,0]
	v_pk_add_f32 v[26:27], v[26:27], v[26:27] op_sel:[0,1] op_sel_hi:[1,0]
	v_mov_b32_e32 v43, v51
	v_mov_b32_e32 v45, v54
	v_mov_b32_e32 v33, v57
	v_mov_b32_e32 v27, v58
	v_pk_add_f32 v[28:29], v[42:43], v[44:45]
	v_pk_add_f32 v[26:27], v[26:27], v[32:33]
	v_pk_add_f32 v[30:31], v[30:31], v[38:39]
	v_pk_add_f32 v[26:27], v[26:27], v[28:29]
	s_waitcnt vmcnt(16)
	v_mul_f32_e32 v59, v111, v111
	v_mul_f32_e32 v60, v110, v110
	v_pk_add_f32 v[30:31], v[30:31], v[30:31] op_sel:[0,1] op_sel_hi:[1,0]
	v_pk_add_f32 v[26:27], v[26:27], v[26:27] op_sel:[0,1] op_sel_hi:[1,0]
	v_mov_b32_e32 v31, v59
	v_mov_b32_e32 v27, v60
	v_mul_f32_e32 v48, v119, v119
	v_mul_f32_e32 v50, v121, v121
	s_waitcnt vmcnt(15)
	v_mov_b32_e32 v40, v103
	s_waitcnt vmcnt(14)
	v_mov_b32_e32 v41, v115
	v_pk_add_f32 v[26:27], v[26:27], v[30:31]
	v_mov_b32_e32 v30, v105
	v_mov_b32_e32 v31, v117
	v_mul_f32_e32 v55, v112, v112
	v_mul_f32_e32 v56, v113, v113
	v_pk_fma_f32 v[46:47], v[118:119], v[118:119], v[48:49] op_sel_hi:[1,1,0]
	v_pk_fma_f32 v[48:49], v[120:121], v[120:121], v[50:51] op_sel_hi:[1,1,0]
	v_mov_b32_e32 v38, v102
	v_mov_b32_e32 v39, v114
	v_mov_b32_e32 v42, v104
	v_pk_mul_f32 v[32:33], v[40:41], v[40:41]
	v_mov_b32_e32 v43, v116
	v_pk_mul_f32 v[30:31], v[30:31], v[30:31]
	v_mov_b32_e32 v47, v55
	v_mov_b32_e32 v49, v56
	v_pk_fma_f32 v[28:29], v[38:39], v[38:39], v[32:33]
	v_pk_fma_f32 v[30:31], v[42:43], v[42:43], v[30:31]
	v_pk_add_f32 v[36:37], v[46:47], v[48:49]
	v_pk_add_f32 v[28:29], v[28:29], v[30:31]
	s_waitcnt vmcnt(13)
	v_pk_mul_f32 v[30:31], v[108:109], v[108:109]
	v_pk_mul_f32 v[32:33], v[106:107], v[106:107]
	v_pk_add_f32 v[26:27], v[26:27], v[36:37]
	v_pk_mov_b32 v[36:37], v[32:33], v[30:31] op_sel:[1,0]
	v_mov_b32_e32 v33, v31
	v_pk_add_f32 v[30:31], v[36:37], v[32:33]
	v_pk_add_f32 v[28:29], v[28:29], v[28:29] op_sel:[0,1] op_sel_hi:[1,0]
	v_pk_add_f32 v[30:31], v[30:31], v[30:31] op_sel:[0,1] op_sel_hi:[1,0]
	s_waitcnt vmcnt(3)
	v_mov_b32_e32 v22, v166
	v_mov_b32_e32 v23, v167
	v_mov_b32_e32 v24, v168
	v_mov_b32_e32 v25, v169
	v_mul_f32_e32 v29, v98, v98
	v_mul_f32_e32 v31, v99, v99
	v_pk_add_f32 v[28:29], v[28:29], v[30:31]
	s_waitcnt vmcnt(0)
	v_mul_f32_e32 v30, v123, v123
	v_mul_f32_e32 v32, v125, v125
	v_pk_fma_f32 v[30:31], v[122:123], v[122:123], v[30:31] op_sel_hi:[1,1,0]
	v_pk_fma_f32 v[32:33], v[124:125], v[124:125], v[32:33] op_sel_hi:[1,1,0]
	v_mul_f32_e32 v31, v100, v100
	v_mul_f32_e32 v33, v101, v101
	v_pk_add_f32 v[30:31], v[30:31], v[32:33]
	v_pk_mul_f32 v[32:33], v[94:95], v[94:95]
	v_pk_add_f32 v[28:29], v[28:29], v[30:31]
	v_pk_mul_f32 v[30:31], v[96:97], v[96:97]
	v_pk_add_f32 v[28:29], v[28:29], v[28:29] op_sel:[0,1] op_sel_hi:[1,0]
	v_pk_mov_b32 v[36:37], v[32:33], v[30:31] op_sel:[1,0]
	v_mov_b32_e32 v33, v31
	v_pk_add_f32 v[30:31], v[36:37], v[32:33]
	v_mul_f32_e32 v29, v62, v62
	v_pk_add_f32 v[30:31], v[30:31], v[30:31] op_sel:[0,1] op_sel_hi:[1,0]
	v_mul_f32_e32 v32, v93, v93
	v_mul_f32_e32 v31, v63, v63
	v_pk_add_f32 v[28:29], v[28:29], v[30:31]
	v_mul_f32_e32 v30, v91, v91
	v_pk_fma_f32 v[30:31], v[90:91], v[90:91], v[30:31] op_sel_hi:[1,1,0]
	v_pk_fma_f32 v[32:33], v[92:93], v[92:93], v[32:33] op_sel_hi:[1,1,0]
	v_mul_f32_e32 v31, v64, v64
	v_mul_f32_e32 v33, v65, v65
	v_pk_add_f32 v[30:31], v[30:31], v[32:33]
	global_load_dwordx4 v[54:57], v130, s[44:45] nt
	v_pk_add_f32 v[28:29], v[28:29], v[30:31]
	v_mov_b32_e32 v31, v26
	v_mov_b32_e32 v30, v28
	v_mov_b32_e32 v26, v29
	v_pk_add_f32 v[26:27], v[30:31], v[26:27]
	v_mbcnt_hi_u32_b32 v30, -1, v165
	v_and_b32_e32 v28, 64, v30
	v_add_u32_e32 v31, 64, v28
	v_xor_b32_e32 v28, 1, v30
	v_cmp_lt_i32_e32 vcc, v28, v31
	s_nop 1
	v_cndmask_b32_e32 v28, v30, v28, vcc
	v_lshlrev_b32_e32 v127, 2, v28
	ds_bpermute_b32 v29, v127, v27
	ds_bpermute_b32 v28, v127, v26
	s_waitcnt lgkmcnt(0)
	v_pk_add_f32 v[26:27], v[26:27], v[28:29]
	v_xor_b32_e32 v28, 2, v30
	v_cmp_lt_i32_e32 vcc, v28, v31
	s_nop 1
	v_cndmask_b32_e32 v28, v30, v28, vcc
	v_lshlrev_b32_e32 v129, 2, v28
	ds_bpermute_b32 v29, v129, v27
	ds_bpermute_b32 v28, v129, v26
	s_waitcnt lgkmcnt(0)
	v_pk_add_f32 v[26:27], v[26:27], v[28:29]
	v_xor_b32_e32 v28, 4, v30
	v_cmp_lt_i32_e32 vcc, v28, v31
	s_nop 1
	v_cndmask_b32_e32 v28, v30, v28, vcc
	v_lshlrev_b32_e32 v137, 2, v28
	ds_bpermute_b32 v29, v137, v27
	ds_bpermute_b32 v28, v137, v26
	s_waitcnt lgkmcnt(0)
	v_pk_add_f32 v[26:27], v[26:27], v[28:29]
	v_xor_b32_e32 v28, 8, v30
	v_cmp_lt_i32_e32 vcc, v28, v31
	s_nop 1
	v_cndmask_b32_e32 v28, v30, v28, vcc
	v_lshlrev_b32_e32 v138, 2, v28
	ds_bpermute_b32 v29, v138, v27
	ds_bpermute_b32 v28, v138, v26
	s_waitcnt lgkmcnt(0)
	v_pk_add_f32 v[26:27], v[26:27], v[28:29]
	v_xor_b32_e32 v28, 16, v30
	v_cmp_lt_i32_e32 vcc, v28, v31
	s_nop 1
	v_cndmask_b32_e32 v28, v30, v28, vcc
	v_lshlrev_b32_e32 v139, 2, v28
	ds_bpermute_b32 v29, v139, v27
	ds_bpermute_b32 v28, v139, v26
	s_waitcnt lgkmcnt(0)
	v_pk_add_f32 v[26:27], v[26:27], v[28:29]
	v_xor_b32_e32 v28, 32, v30
	v_cmp_lt_i32_e32 vcc, v28, v31
	s_nop 1
	v_cndmask_b32_e32 v28, v30, v28, vcc
	v_lshlrev_b32_e32 v140, 2, v28
	ds_bpermute_b32 v29, v140, v27
	ds_bpermute_b32 v28, v140, v26
	s_waitcnt lgkmcnt(0)
	v_pk_add_f32 v[26:27], v[26:27], v[28:29]
	s_nop 0
	v_pk_fma_f32 v[134:135], v[26:27], s[40:41], v[132:133] op_sel_hi:[1,0,0]
	s_nop 0
	v_mul_f32_e32 v26, 0x4b800000, v135
	v_cmp_gt_f32_e32 vcc, s3, v135
	s_nop 1
	v_cndmask_b32_e32 v26, v135, v26, vcc
	v_rsq_f32_e32 v26, v26
	s_nop 0
	v_mul_f32_e32 v27, 0x45800000, v26
	v_cndmask_b32_e32 v136, v26, v27, vcc
	v_pk_mul_f32 v[18:19], v[18:19], v[136:137] op_sel_hi:[1,0]
	v_pk_mul_f32 v[20:21], v[20:21], v[136:137] op_sel_hi:[1,0]
	v_pk_mul_f32 v[144:145], v[22:23], v[18:19]
	v_pk_mul_f32 v[142:143], v[24:25], v[20:21]
	global_load_dwordx4 v[70:73], v34, s[44:45] nt
	global_load_dwordx4 v[30:33], v34, s[46:47] nt
	global_load_dwordx4 v[66:69], v1, s[44:45] nt
	global_load_dwordx4 v[26:29], v1, s[46:47] nt
	global_load_dwordx4 v[58:61], v35, s[44:45] nt
	global_load_dwordx4 v[22:25], v35, s[46:47] nt
	global_load_dwordx4 v[50:53], v78, s[44:45] nt
	global_load_dwordx4 v[18:21], v78, s[46:47] nt
	global_load_dwordx4 v[86:89], v130, s[44:45] offset:1024 nt
	global_load_dwordx4 v[82:85], v130, s[44:45] offset:2048 nt
	s_nop 0
	global_load_dwordx4 v[78:81], v130, s[44:45] offset:3072 nt
	global_load_dwordx4 v[46:49], v130, s[46:47] nt
	global_load_dwordx4 v[42:45], v130, s[46:47] offset:1024 nt
	global_load_dwordx4 v[38:41], v130, s[46:47] offset:2048 nt
	global_load_dwordx4 v[34:37], v130, s[46:47] offset:3072 nt
	s_lshl_b64 s[44:45], s[24:25], 12
	s_add_u32 s44, s36, s44
	s_addc_u32 s45, s37, s45
	v_cvt_pk_bf16_f32 v144, v144, v145
	v_cvt_pk_bf16_f32 v145, v142, v143
	global_store_dwordx2 v126, v[144:145], s[44:45]
	v_pk_mul_f32 v[74:75], v[74:75], v[136:137] op_sel_hi:[1,0]
	v_pk_mul_f32 v[76:77], v[76:77], v[136:137] op_sel_hi:[1,0]
	v_pk_mul_f32 v[14:15], v[14:15], v[136:137] op_sel_hi:[1,0]
	v_pk_mul_f32 v[16:17], v[16:17], v[136:137] op_sel_hi:[1,0]
	v_pk_mul_f32 v[10:11], v[10:11], v[136:137] op_sel_hi:[1,0]
	v_pk_mul_f32 v[12:13], v[12:13], v[136:137] op_sel_hi:[1,0]
	v_pk_mul_f32 v[6:7], v[6:7], v[136:137] op_sel_hi:[1,0]
	v_pk_mul_f32 v[8:9], v[8:9], v[136:137] op_sel_hi:[1,0]
	v_pk_mul_f32 v[2:3], v[2:3], v[136:137] op_sel_hi:[1,0]
	v_pk_mul_f32 v[4:5], v[4:5], v[136:137] op_sel_hi:[1,0]
	v_mul_f32_e32 v1, 0x4b800000, v134
	s_lshl_b64 s[42:43], s[42:43], 12
	s_add_u32 s42, s36, s42
	s_addc_u32 s43, s37, s43
	s_lshl_b64 s[4:5], s[4:5], 12
	s_add_u32 s4, s36, s4
	s_addc_u32 s5, s37, s5
	s_waitcnt vmcnt(1)
	v_mov_b32_e32 v142, v170
	v_mov_b32_e32 v143, v171
	v_mov_b32_e32 v144, v172
	v_mov_b32_e32 v145, v173
	v_pk_mul_f32 v[74:75], v[142:143], v[74:75]
	v_pk_mul_f32 v[76:77], v[144:145], v[76:77]
	v_cvt_pk_bf16_f32 v74, v74, v75
	s_nop 0
	v_cvt_pk_bf16_f32 v75, v76, v77
	global_store_dwordx2 v126, v[74:75], s[44:45] offset:512
	v_mov_b32_e32 v74, v174
	v_mov_b32_e32 v75, v175
	v_mov_b32_e32 v76, v176
	v_mov_b32_e32 v77, v177
	v_pk_mul_f32 v[14:15], v[14:15], v[74:75]
	v_pk_mul_f32 v[16:17], v[16:17], v[76:77]
	v_cvt_pk_bf16_f32 v14, v14, v15
	s_nop 0
	v_cvt_pk_bf16_f32 v15, v16, v17
	global_store_dwordx2 v126, v[14:15], s[44:45] offset:1024
	v_lshl_add_u64 v[14:15], s[34:35], 0, v[130:131]
	v_add_co_u32_e32 v14, vcc, s12, v14
	v_pk_mul_f32 v[16:17], v[66:67], v[66:67]
	s_nop 0
	v_addc_co_u32_e32 v15, vcc, 0, v15, vcc
	v_cmp_gt_f32_e32 vcc, s3, v134
	v_mov_b32_e32 v74, v178
	v_mov_b32_e32 v75, v179
	v_mov_b32_e32 v76, v180
	v_mov_b32_e32 v77, v181
	v_pk_mul_f32 v[10:11], v[10:11], v[74:75]
	v_pk_mul_f32 v[12:13], v[12:13], v[76:77]
	v_cvt_pk_bf16_f32 v10, v10, v11
	v_cndmask_b32_e32 v1, v134, v1, vcc
	v_cvt_pk_bf16_f32 v11, v12, v13
	global_store_dwordx2 v126, v[10:11], s[44:45] offset:1536
	v_rsq_f32_e32 v1, v1
	v_mov_b32_e32 v76, v55
	v_mov_b32_e32 v77, v87
	v_mov_b32_e32 v74, v54
	v_mov_b32_e32 v75, v86
	v_mov_b32_e32 v10, v182
	v_mov_b32_e32 v11, v183
	v_mov_b32_e32 v12, v184
	v_mov_b32_e32 v13, v185
	v_pk_mul_f32 v[6:7], v[6:7], v[10:11]
	v_pk_mul_f32 v[8:9], v[8:9], v[12:13]
	v_cvt_pk_bf16_f32 v6, v6, v7
	v_pk_mul_f32 v[12:13], v[68:69], v[68:69]
	v_cvt_pk_bf16_f32 v7, v8, v9
	global_store_dwordx2 v126, v[6:7], s[44:45] offset:2048
	v_mov_b32_e32 v6, v186
	v_mov_b32_e32 v7, v187
	v_mov_b32_e32 v8, v188
	v_mov_b32_e32 v9, v189
	v_pk_mul_f32 v[2:3], v[2:3], v[6:7]
	v_pk_mul_f32 v[4:5], v[4:5], v[8:9]
	v_cvt_pk_bf16_f32 v2, v2, v3
	v_pk_mul_f32 v[6:7], v[118:119], v[136:137] op_sel_hi:[1,0]
	v_cvt_pk_bf16_f32 v3, v4, v5
	global_store_dwordx2 v126, v[2:3], s[44:45] offset:2560
	v_pk_mul_f32 v[8:9], v[120:121], v[136:137] op_sel_hi:[1,0]
	v_mul_f32_e32 v118, v31, v31
	v_mul_f32_e32 v119, v30, v30
	v_mul_f32_e32 v120, v19, v19
	v_mul_f32_e32 v121, v18, v18
	v_mov_b32_e32 v2, v190
	v_mov_b32_e32 v3, v191
	v_mov_b32_e32 v4, v192
	v_mov_b32_e32 v5, v193
	v_pk_mul_f32 v[2:3], v[6:7], v[2:3]
	v_pk_mul_f32 v[4:5], v[8:9], v[4:5]
	v_cvt_pk_bf16_f32 v2, v2, v3
	v_pk_mul_f32 v[6:7], v[110:111], v[136:137] op_sel_hi:[1,0]
	v_cvt_pk_bf16_f32 v3, v4, v5
	global_store_dwordx2 v126, v[2:3], s[44:45] offset:3072
	v_pk_mul_f32 v[8:9], v[112:113], v[136:137] op_sel_hi:[1,0]
	v_mul_f32_e32 v111, v70, v70
	v_mul_f32_e32 v110, v25, v25
	v_mov_b32_e32 v2, v200
	v_mov_b32_e32 v3, v201
	v_mov_b32_e32 v4, v202
	v_mov_b32_e32 v5, v203
	v_pk_mul_f32 v[2:3], v[6:7], v[2:3]
	v_pk_mul_f32 v[4:5], v[8:9], v[4:5]
	v_cvt_pk_bf16_f32 v2, v2, v3
	v_mul_f32_e32 v6, 0x45800000, v1
	v_cvt_pk_bf16_f32 v3, v4, v5
	global_store_dwordx2 v126, v[2:3], s[44:45] offset:3584
	v_cndmask_b32_e32 v6, v1, v6, vcc
	v_pk_mul_f32 v[8:9], v[102:103], v[6:7] op_sel_hi:[1,0]
	v_pk_mul_f32 v[10:11], v[104:105], v[6:7] op_sel_hi:[1,0]
	v_mul_f32_e32 v1, v72, v72
	v_mul_f32_e32 v104, v53, v53
	v_mul_f32_e32 v105, v71, v71
	v_mov_b32_e32 v2, v166
	v_mov_b32_e32 v3, v167
	v_mov_b32_e32 v4, v168
	v_mov_b32_e32 v5, v169
	v_pk_mul_f32 v[2:3], v[8:9], v[2:3]
	v_pk_mul_f32 v[4:5], v[10:11], v[4:5]
	v_cvt_pk_bf16_f32 v2, v2, v3
	v_pk_mul_f32 v[8:9], v[114:115], v[6:7] op_sel_hi:[1,0]
	v_cvt_pk_bf16_f32 v3, v4, v5
	global_store_dwordx2 v126, v[2:3], s[42:43]
	v_pk_mul_f32 v[10:11], v[116:117], v[6:7] op_sel_hi:[1,0]
	v_mul_f32_e32 v114, v51, v51
	v_mul_f32_e32 v115, v50, v50
	v_mul_f32_e32 v116, v20, v20
	v_mul_f32_e32 v117, v21, v21
	v_mov_b32_e32 v2, v170
	v_mov_b32_e32 v3, v171
	v_mov_b32_e32 v4, v172
	v_mov_b32_e32 v5, v173
	v_pk_mul_f32 v[2:3], v[8:9], v[2:3]
	v_pk_mul_f32 v[4:5], v[10:11], v[4:5]
	v_cvt_pk_bf16_f32 v2, v2, v3
	v_pk_mul_f32 v[8:9], v[106:107], v[6:7] op_sel_hi:[1,0]
	v_cvt_pk_bf16_f32 v3, v4, v5
	global_store_dwordx2 v126, v[2:3], s[42:43] offset:512
	v_pk_mul_f32 v[10:11], v[108:109], v[6:7] op_sel_hi:[1,0]
	v_mul_f32_e32 v106, v37, v37
	v_mul_f32_e32 v108, v23, v23
	v_mov_b32_e32 v2, v174
	v_mov_b32_e32 v3, v175
	v_mov_b32_e32 v4, v176
	v_mov_b32_e32 v5, v177
	v_pk_mul_f32 v[2:3], v[8:9], v[2:3]
	v_pk_mul_f32 v[4:5], v[10:11], v[4:5]
	v_cvt_pk_bf16_f32 v2, v2, v3
	v_pk_mul_f32 v[8:9], v[122:123], v[6:7] op_sel_hi:[1,0]
	v_cvt_pk_bf16_f32 v3, v4, v5
	global_store_dwordx2 v126, v[2:3], s[42:43] offset:1024
	v_pk_mul_f32 v[10:11], v[124:125], v[6:7] op_sel_hi:[1,0]
	v_mov_b32_e32 v2, v178
	v_mov_b32_e32 v3, v179
	v_mov_b32_e32 v4, v180
	v_mov_b32_e32 v5, v181
	v_pk_mul_f32 v[2:3], v[8:9], v[2:3]
	v_pk_mul_f32 v[4:5], v[10:11], v[4:5]
	v_cvt_pk_bf16_f32 v2, v2, v3
	v_pk_mul_f32 v[8:9], v[98:99], v[6:7] op_sel_hi:[1,0]
	v_cvt_pk_bf16_f32 v3, v4, v5
	global_store_dwordx2 v126, v[2:3], s[42:43] offset:1536
	v_pk_mul_f32 v[10:11], v[100:101], v[6:7] op_sel_hi:[1,0]
	v_mul_f32_e32 v98, v79, v79
	v_mul_f32_e32 v100, v81, v81
	v_mul_f32_e32 v101, v52, v52
	v_mov_b32_e32 v2, v182
	v_mov_b32_e32 v3, v183
	v_mov_b32_e32 v4, v184
	v_mov_b32_e32 v5, v185
	v_pk_mul_f32 v[2:3], v[8:9], v[2:3]
	v_pk_mul_f32 v[4:5], v[10:11], v[4:5]
	v_cvt_pk_bf16_f32 v2, v2, v3
	v_pk_mul_f32 v[8:9], v[94:95], v[6:7] op_sel_hi:[1,0]
	v_cvt_pk_bf16_f32 v3, v4, v5
	global_store_dwordx2 v126, v[2:3], s[42:43] offset:2048
	v_pk_mul_f32 v[10:11], v[96:97], v[6:7] op_sel_hi:[1,0]
	v_mul_f32_e32 v7, v73, v73
	v_pk_mul_f32 v[90:91], v[90:91], v[6:7] op_sel_hi:[1,0]
	v_pk_mul_f32 v[92:93], v[92:93], v[6:7] op_sel_hi:[1,0]
	v_mov_b32_e32 v96, v57
	v_mov_b32_e32 v97, v89
	v_mov_b32_e32 v94, v56
	v_mov_b32_e32 v95, v88
	v_mov_b32_e32 v2, v186
	v_mov_b32_e32 v3, v187
	v_mov_b32_e32 v4, v188
	v_mov_b32_e32 v5, v189
	v_pk_mul_f32 v[2:3], v[8:9], v[2:3]
	v_pk_mul_f32 v[4:5], v[10:11], v[4:5]
	v_cvt_pk_bf16_f32 v2, v2, v3
	v_pk_mul_f32 v[8:9], v[84:85], v[84:85]
	v_cvt_pk_bf16_f32 v3, v4, v5
	global_store_dwordx2 v126, v[2:3], s[42:43] offset:2560
	v_pk_mul_f32 v[10:11], v[82:83], v[82:83]
	v_mov_b32_e32 v2, v190
	v_mov_b32_e32 v3, v191
	v_mov_b32_e32 v4, v192
	v_mov_b32_e32 v5, v193
	v_pk_mul_f32 v[2:3], v[90:91], v[2:3]
	v_pk_mul_f32 v[4:5], v[92:93], v[4:5]
	v_cvt_pk_bf16_f32 v2, v2, v3
	v_mul_f32_e32 v90, v59, v59
	v_cvt_pk_bf16_f32 v3, v4, v5
	global_store_dwordx2 v126, v[2:3], s[42:43] offset:3072
	v_mul_f32_e32 v92, v61, v61
	v_pk_mov_b32 v[102:103], v[10:11], v[8:9] op_sel:[1,0]
	v_mov_b32_e32 v11, v9
	v_pk_mov_b32 v[8:9], v[16:17], v[12:13] op_sel:[1,0]
	v_mov_b32_e32 v17, v13
	v_pk_mul_f32 v[12:13], v[76:77], v[76:77]
	v_pk_mul_f32 v[76:77], v[96:97], v[96:97]
	v_pk_fma_f32 v[96:97], v[78:79], v[78:79], v[98:99] op_sel_hi:[1,1,0]
	v_pk_fma_f32 v[98:99], v[80:81], v[80:81], v[100:101] op_sel_hi:[1,1,0]
	v_pk_fma_f32 v[90:91], v[58:59], v[58:59], v[90:91] op_sel_hi:[1,1,0]
	v_pk_fma_f32 v[92:93], v[60:61], v[60:61], v[92:93] op_sel_hi:[1,1,0]
	v_pk_fma_f32 v[12:13], v[74:75], v[74:75], v[12:13]
	v_pk_fma_f32 v[74:75], v[94:95], v[94:95], v[76:77]
	v_pk_add_f32 v[10:11], v[102:103], v[10:11]
	v_mov_b32_e32 v97, v1
	v_mov_b32_e32 v99, v7
	v_mov_b32_e32 v91, v101
	v_mov_b32_e32 v93, v104
	v_pk_add_f32 v[8:9], v[8:9], v[16:17]
	v_pk_add_f32 v[12:13], v[12:13], v[74:75]
	v_pk_add_f32 v[16:17], v[96:97], v[98:99]
	v_pk_add_f32 v[74:75], v[90:91], v[92:93]
	v_pk_mul_f32 v[76:77], v[40:41], v[40:41]
	v_pk_mul_f32 v[90:91], v[38:39], v[38:39]
	v_pk_mul_f32 v[92:93], v[28:29], v[28:29]
	v_pk_mul_f32 v[94:95], v[26:27], v[26:27]
	v_mov_b32_e32 v98, v47
	v_mov_b32_e32 v99, v43
	v_mov_b32_e32 v102, v49
	v_mov_b32_e32 v103, v45
	v_pk_add_f32 v[10:11], v[10:11], v[10:11] op_sel:[0,1] op_sel_hi:[1,0]
	v_mul_f32_e32 v104, v35, v35
	v_mul_f32_e32 v7, v33, v33
	v_pk_mov_b32 v[112:113], v[90:91], v[76:77] op_sel:[1,0]
	v_mov_b32_e32 v91, v77
	v_pk_mov_b32 v[76:77], v[94:95], v[92:93] op_sel:[1,0]
	v_mov_b32_e32 v95, v93
	v_pk_mul_f32 v[92:93], v[98:99], v[98:99]
	v_pk_mul_f32 v[98:99], v[102:103], v[102:103]
	v_mov_b32_e32 v11, v105
	v_pk_fma_f32 v[102:103], v[34:35], v[34:35], v[104:105] op_sel_hi:[1,1,0]
	v_pk_fma_f32 v[104:105], v[36:37], v[36:37], v[106:107] op_sel_hi:[1,1,0]
	v_pk_mul_f32 v[62:63], v[62:63], v[6:7] op_sel_hi:[1,0]
	v_mov_b32_e32 v105, v7
	v_pk_mul_f32 v[6:7], v[64:65], v[6:7] op_sel_hi:[1,0]
	v_mov_b32_e32 v96, v46
	v_mov_b32_e32 v97, v42
	v_mov_b32_e32 v100, v48
	v_mov_b32_e32 v101, v44
	v_pk_add_f32 v[12:13], v[12:13], v[12:13] op_sel:[0,1] op_sel_hi:[1,0]
	v_pk_fma_f32 v[92:93], v[96:97], v[96:97], v[92:93]
	v_pk_fma_f32 v[96:97], v[100:101], v[100:101], v[98:99]
	v_mov_b32_e32 v13, v111
	v_pk_add_f32 v[90:91], v[112:113], v[90:91]
	v_mul_f32_e32 v1, v32, v32
	v_pk_add_f32 v[64:65], v[90:91], v[90:91] op_sel:[0,1] op_sel_hi:[1,0]
	v_pk_add_f32 v[8:9], v[8:9], v[8:9] op_sel:[0,1] op_sel_hi:[1,0]
	v_mov_b32_e32 v103, v1
	v_mov_b32_e32 v65, v118
	v_mov_b32_e32 v9, v114
	v_pk_add_f32 v[76:77], v[76:77], v[94:95]
	v_pk_fma_f32 v[106:107], v[22:23], v[22:23], v[108:109] op_sel_hi:[1,1,0]
	v_pk_fma_f32 v[108:109], v[24:25], v[24:25], v[110:111] op_sel_hi:[1,1,0]
	v_pk_add_f32 v[76:77], v[76:77], v[76:77] op_sel:[0,1] op_sel_hi:[1,0]
	v_mov_b32_e32 v107, v116
	v_mov_b32_e32 v109, v117
	v_mov_b32_e32 v77, v120
	v_mov_b32_e32 v2, v200
	v_mov_b32_e32 v3, v201
	v_mov_b32_e32 v4, v202
	v_mov_b32_e32 v5, v203
	v_pk_mul_f32 v[2:3], v[62:63], v[2:3]
	v_pk_mul_f32 v[4:5], v[6:7], v[4:5]
	v_cvt_pk_bf16_f32 v2, v2, v3
	v_pk_add_f32 v[6:7], v[12:13], v[10:11]
	v_cvt_pk_bf16_f32 v3, v4, v5
	global_store_dwordx2 v126, v[2:3], s[42:43] offset:3584
	v_pk_add_f32 v[10:11], v[92:93], v[96:97]
	v_pk_add_f32 v[6:7], v[6:7], v[16:17]
	v_pk_add_f32 v[10:11], v[10:11], v[10:11] op_sel:[0,1] op_sel_hi:[1,0]
	v_pk_add_f32 v[6:7], v[6:7], v[6:7] op_sel:[0,1] op_sel_hi:[1,0]
	v_mov_b32_e32 v11, v119
	v_pk_add_f32 v[12:13], v[102:103], v[104:105]
	v_pk_add_f32 v[10:11], v[10:11], v[64:65]
	v_mov_b32_e32 v7, v115
	v_pk_add_f32 v[6:7], v[6:7], v[8:9]
	v_pk_add_f32 v[8:9], v[10:11], v[12:13]
	v_pk_add_f32 v[62:63], v[106:107], v[108:109]
	v_pk_add_f32 v[8:9], v[8:9], v[8:9] op_sel:[0,1] op_sel_hi:[1,0]
	v_pk_add_f32 v[6:7], v[6:7], v[74:75]
	v_mov_b32_e32 v9, v121
	v_pk_add_f32 v[8:9], v[8:9], v[76:77]
	v_mov_b32_e32 v11, v6
	v_pk_add_f32 v[8:9], v[8:9], v[62:63]
	s_nop 0
	v_mov_b32_e32 v10, v8
	v_mov_b32_e32 v6, v9
	v_pk_add_f32 v[6:7], v[10:11], v[6:7]
	ds_bpermute_b32 v9, v127, v7
	ds_bpermute_b32 v8, v127, v6
	s_waitcnt lgkmcnt(0)
	v_pk_add_f32 v[6:7], v[6:7], v[8:9]
	ds_bpermute_b32 v9, v129, v7
	ds_bpermute_b32 v8, v129, v6
	s_waitcnt lgkmcnt(0)
	v_pk_add_f32 v[6:7], v[6:7], v[8:9]
	ds_bpermute_b32 v9, v137, v7
	ds_bpermute_b32 v8, v137, v6
	s_waitcnt lgkmcnt(0)
	v_pk_add_f32 v[6:7], v[6:7], v[8:9]
	ds_bpermute_b32 v9, v138, v7
	ds_bpermute_b32 v8, v138, v6
	s_waitcnt lgkmcnt(0)
	v_pk_add_f32 v[6:7], v[6:7], v[8:9]
	ds_bpermute_b32 v9, v139, v7
	ds_bpermute_b32 v8, v139, v6
	s_waitcnt lgkmcnt(0)
	v_pk_add_f32 v[6:7], v[6:7], v[8:9]
	ds_bpermute_b32 v9, v140, v7
	ds_bpermute_b32 v8, v140, v6
	s_waitcnt lgkmcnt(0)
	v_pk_add_f32 v[6:7], v[6:7], v[8:9]
	s_nop 0
	v_pk_fma_f32 v[6:7], v[6:7], s[40:41], v[132:133] op_sel_hi:[1,0,0]
	s_nop 0
	v_mul_f32_e32 v1, 0x4b800000, v7
	v_cmp_gt_f32_e32 vcc, s3, v7
	s_nop 1
	v_cndmask_b32_e32 v1, v7, v1, vcc
	v_rsq_f32_e32 v1, v1
	s_nop 0
	v_mul_f32_e32 v7, 0x45800000, v1
	v_cndmask_b32_e32 v8, v1, v7, vcc
	v_pk_mul_f32 v[10:11], v[54:55], v[8:9] op_sel_hi:[1,0]
	v_pk_mul_f32 v[12:13], v[56:57], v[8:9] op_sel_hi:[1,0]
	v_mul_f32_e32 v1, 0x4b800000, v6
	v_mov_b32_e32 v2, v166
	v_mov_b32_e32 v3, v167
	v_mov_b32_e32 v4, v168
	v_mov_b32_e32 v5, v169
	v_pk_mul_f32 v[2:3], v[10:11], v[2:3]
	v_pk_mul_f32 v[4:5], v[12:13], v[4:5]
	v_cvt_pk_bf16_f32 v2, v2, v3
	v_pk_mul_f32 v[10:11], v[86:87], v[8:9] op_sel_hi:[1,0]
	v_cvt_pk_bf16_f32 v3, v4, v5
	global_store_dwordx2 v126, v[2:3], s[4:5]
	v_pk_mul_f32 v[12:13], v[88:89], v[8:9] op_sel_hi:[1,0]
	v_cmp_gt_f32_e32 vcc, s3, v6
	v_mov_b32_e32 v2, v170
	v_mov_b32_e32 v3, v171
	v_mov_b32_e32 v4, v172
	v_mov_b32_e32 v5, v173
	v_pk_mul_f32 v[2:3], v[10:11], v[2:3]
	v_pk_mul_f32 v[4:5], v[12:13], v[4:5]
	v_cvt_pk_bf16_f32 v2, v2, v3
	v_pk_mul_f32 v[10:11], v[82:83], v[8:9] op_sel_hi:[1,0]
	v_cvt_pk_bf16_f32 v3, v4, v5
	global_store_dwordx2 v126, v[2:3], s[4:5] offset:512
	v_pk_mul_f32 v[12:13], v[84:85], v[8:9] op_sel_hi:[1,0]
	v_cndmask_b32_e32 v1, v6, v1, vcc
	v_rsq_f32_e32 v1, v1
	v_mov_b32_e32 v2, v174
	v_mov_b32_e32 v3, v175
	v_mov_b32_e32 v4, v176
	v_mov_b32_e32 v5, v177
	v_pk_mul_f32 v[2:3], v[10:11], v[2:3]
	v_pk_mul_f32 v[4:5], v[12:13], v[4:5]
	v_cvt_pk_bf16_f32 v2, v2, v3
	v_pk_mul_f32 v[10:11], v[78:79], v[8:9] op_sel_hi:[1,0]
	v_cvt_pk_bf16_f32 v3, v4, v5
	global_store_dwordx2 v126, v[2:3], s[4:5] offset:1024
	v_pk_mul_f32 v[12:13], v[80:81], v[8:9] op_sel_hi:[1,0]
	v_mul_f32_e32 v6, 0x45800000, v1
	v_cndmask_b32_e32 v6, v1, v6, vcc
	v_mov_b32_e32 v2, v178
	v_mov_b32_e32 v3, v179
	v_mov_b32_e32 v4, v180
	v_mov_b32_e32 v5, v181
	v_pk_mul_f32 v[2:3], v[10:11], v[2:3]
	v_pk_mul_f32 v[4:5], v[12:13], v[4:5]
	v_cvt_pk_bf16_f32 v2, v2, v3
	v_pk_mul_f32 v[10:11], v[70:71], v[8:9] op_sel_hi:[1,0]
	v_cvt_pk_bf16_f32 v3, v4, v5
	global_store_dwordx2 v126, v[2:3], s[4:5] offset:1536
	v_pk_mul_f32 v[12:13], v[72:73], v[8:9] op_sel_hi:[1,0]
	v_mov_b32_e32 v2, v182
	v_mov_b32_e32 v3, v183
	v_mov_b32_e32 v4, v184
	v_mov_b32_e32 v5, v185
	v_pk_mul_f32 v[2:3], v[10:11], v[2:3]
	v_pk_mul_f32 v[4:5], v[12:13], v[4:5]
	v_cvt_pk_bf16_f32 v2, v2, v3
	v_pk_mul_f32 v[10:11], v[66:67], v[8:9] op_sel_hi:[1,0]
	v_cvt_pk_bf16_f32 v3, v4, v5
	global_store_dwordx2 v126, v[2:3], s[4:5] offset:2048
	v_pk_mul_f32 v[12:13], v[68:69], v[8:9] op_sel_hi:[1,0]
	v_mov_b32_e32 v2, v186
	v_mov_b32_e32 v3, v187
	v_mov_b32_e32 v4, v188
	v_mov_b32_e32 v5, v189
	v_pk_mul_f32 v[2:3], v[10:11], v[2:3]
	v_pk_mul_f32 v[4:5], v[12:13], v[4:5]
	v_cvt_pk_bf16_f32 v2, v2, v3
	v_pk_mul_f32 v[10:11], v[58:59], v[8:9] op_sel_hi:[1,0]
	v_cvt_pk_bf16_f32 v3, v4, v5
	global_store_dwordx2 v126, v[2:3], s[4:5] offset:2560
	v_pk_mul_f32 v[12:13], v[60:61], v[8:9] op_sel_hi:[1,0]
	v_mov_b32_e32 v2, v190
	v_mov_b32_e32 v3, v191
	v_mov_b32_e32 v4, v192
	v_mov_b32_e32 v5, v193
	v_pk_mul_f32 v[2:3], v[10:11], v[2:3]
	v_pk_mul_f32 v[4:5], v[12:13], v[4:5]
	v_cvt_pk_bf16_f32 v2, v2, v3
	v_pk_mul_f32 v[10:11], v[50:51], v[8:9] op_sel_hi:[1,0]
	v_cvt_pk_bf16_f32 v3, v4, v5
	global_store_dwordx2 v126, v[2:3], s[4:5] offset:3072
	v_pk_mul_f32 v[8:9], v[52:53], v[8:9] op_sel_hi:[1,0]
	v_mov_b32_e32 v2, v200
	v_mov_b32_e32 v3, v201
	v_mov_b32_e32 v4, v202
	v_mov_b32_e32 v5, v203
	v_pk_mul_f32 v[2:3], v[10:11], v[2:3]
	v_pk_mul_f32 v[4:5], v[8:9], v[4:5]
	v_cvt_pk_bf16_f32 v2, v2, v3
	v_pk_mul_f32 v[8:9], v[46:47], v[6:7] op_sel_hi:[1,0]
	v_cvt_pk_bf16_f32 v3, v4, v5
	global_store_dwordx2 v126, v[2:3], s[4:5] offset:3584
	s_mov_b32 s4, s28
	v_writelane_b32 v226, s4, 1
	v_pk_mul_f32 v[10:11], v[48:49], v[6:7] op_sel_hi:[1,0]
	v_mov_b32_e32 v2, v166
	v_mov_b32_e32 v3, v167
	v_mov_b32_e32 v4, v168
	v_mov_b32_e32 v5, v169
	v_pk_mul_f32 v[2:3], v[8:9], v[2:3]
	v_writelane_b32 v226, s5, 2
	s_lshl_b64 s[4:5], s[28:29], 12
	s_add_u32 s4, s36, s4
	s_addc_u32 s5, s37, s5
	v_pk_mul_f32 v[4:5], v[10:11], v[4:5]
	v_cvt_pk_bf16_f32 v2, v2, v3
	v_pk_mul_f32 v[8:9], v[42:43], v[6:7] op_sel_hi:[1,0]
	v_cvt_pk_bf16_f32 v3, v4, v5
	global_store_dwordx2 v126, v[2:3], s[4:5]
	v_pk_mul_f32 v[10:11], v[44:45], v[6:7] op_sel_hi:[1,0]
	s_lshl_b32 s3, s26, 5
	s_add_i32 s40, s24, s3
	v_mov_b32_e32 v2, v170
	v_mov_b32_e32 v3, v171
	v_mov_b32_e32 v4, v172
	v_mov_b32_e32 v5, v173
	v_pk_mul_f32 v[2:3], v[8:9], v[2:3]
	v_pk_mul_f32 v[4:5], v[10:11], v[4:5]
	v_cvt_pk_bf16_f32 v2, v2, v3
	v_pk_mul_f32 v[8:9], v[38:39], v[6:7] op_sel_hi:[1,0]
	v_cvt_pk_bf16_f32 v3, v4, v5
	global_store_dwordx2 v126, v[2:3], s[4:5] offset:512
	v_pk_mul_f32 v[10:11], v[40:41], v[6:7] op_sel_hi:[1,0]
	v_mov_b32_e32 v2, v174
	v_mov_b32_e32 v3, v175
	v_mov_b32_e32 v4, v176
	v_mov_b32_e32 v5, v177
	v_pk_mul_f32 v[2:3], v[8:9], v[2:3]
	v_pk_mul_f32 v[4:5], v[10:11], v[4:5]
	v_cvt_pk_bf16_f32 v2, v2, v3
	v_pk_mul_f32 v[8:9], v[34:35], v[6:7] op_sel_hi:[1,0]
	v_cvt_pk_bf16_f32 v3, v4, v5
	global_store_dwordx2 v126, v[2:3], s[4:5] offset:1024
	v_pk_mul_f32 v[10:11], v[36:37], v[6:7] op_sel_hi:[1,0]
	v_mov_b32_e32 v2, v178
	v_mov_b32_e32 v3, v179
	v_mov_b32_e32 v4, v180
	v_mov_b32_e32 v5, v181
	v_pk_mul_f32 v[2:3], v[8:9], v[2:3]
	v_pk_mul_f32 v[4:5], v[10:11], v[4:5]
	v_cvt_pk_bf16_f32 v2, v2, v3
	v_pk_mul_f32 v[8:9], v[30:31], v[6:7] op_sel_hi:[1,0]
	v_cvt_pk_bf16_f32 v3, v4, v5
	global_store_dwordx2 v126, v[2:3], s[4:5] offset:1536
	v_pk_mul_f32 v[10:11], v[32:33], v[6:7] op_sel_hi:[1,0]
	v_mov_b32_e32 v2, v182
	v_mov_b32_e32 v3, v183
	v_mov_b32_e32 v4, v184
	v_mov_b32_e32 v5, v185
	v_pk_mul_f32 v[2:3], v[8:9], v[2:3]
	v_pk_mul_f32 v[4:5], v[10:11], v[4:5]
	v_cvt_pk_bf16_f32 v2, v2, v3
	v_pk_mul_f32 v[8:9], v[26:27], v[6:7] op_sel_hi:[1,0]
	v_cvt_pk_bf16_f32 v3, v4, v5
	global_store_dwordx2 v126, v[2:3], s[4:5] offset:2048
	v_pk_mul_f32 v[10:11], v[28:29], v[6:7] op_sel_hi:[1,0]
	v_mov_b32_e32 v2, v186
	v_mov_b32_e32 v3, v187
	v_mov_b32_e32 v4, v188
	v_mov_b32_e32 v5, v189
	v_pk_mul_f32 v[2:3], v[8:9], v[2:3]
	v_pk_mul_f32 v[4:5], v[10:11], v[4:5]
	v_cvt_pk_bf16_f32 v2, v2, v3
	v_pk_mul_f32 v[8:9], v[22:23], v[6:7] op_sel_hi:[1,0]
	v_cvt_pk_bf16_f32 v3, v4, v5
	global_store_dwordx2 v126, v[2:3], s[4:5] offset:2560
	v_pk_mul_f32 v[10:11], v[24:25], v[6:7] op_sel_hi:[1,0]
	v_mov_b32_e32 v2, v190
	v_mov_b32_e32 v3, v191
	v_mov_b32_e32 v4, v192
	v_mov_b32_e32 v5, v193
	v_pk_mul_f32 v[2:3], v[8:9], v[2:3]
	v_pk_mul_f32 v[4:5], v[10:11], v[4:5]
	v_cvt_pk_bf16_f32 v2, v2, v3
	v_pk_mul_f32 v[8:9], v[18:19], v[6:7] op_sel_hi:[1,0]
	v_cvt_pk_bf16_f32 v3, v4, v5
	global_store_dwordx2 v126, v[2:3], s[4:5] offset:3072
	v_pk_mul_f32 v[6:7], v[20:21], v[6:7] op_sel_hi:[1,0]
	v_mov_b32_e32 v2, v200
	v_mov_b32_e32 v3, v201
	v_mov_b32_e32 v4, v202
	v_mov_b32_e32 v5, v203
	v_pk_mul_f32 v[2:3], v[8:9], v[2:3]
	v_pk_mul_f32 v[4:5], v[6:7], v[4:5]
	v_cvt_pk_bf16_f32 v2, v2, v3
	s_nop 0
	v_cvt_pk_bf16_f32 v3, v4, v5
	global_store_dwordx2 v126, v[2:3], s[4:5] offset:3584
.LBB0_24:
	s_cmpk_lg_i32 s26, 0x100
	s_cbranch_scc1 .Lp0r5_orig
	s_waitcnt lgkmcnt(0)
	v_and_b32_e32 v154, 63, v164
	v_lshlrev_b32_e32 v155, 4, v154
	v_add_u32_e32 v156, 0x1000, v155
	v_lshlrev_b32_e32 v157, 3, v154
	v_lshlrev_b32_e32 v158, 2, v154
	s_cmpk_lt_u32 s24, 0x400
	s_cselect_b32 s98, s10, s14
	s_cselect_b32 s99, s11, s15
	s_cselect_b32 s100, s34, s38
	s_cselect_b32 s101, s35, s39
	s_and_b32 s93, s24, 0x3ff
	s_lshl_b32 s93, s93, 13
	s_add_u32 s98, s98, s93
	s_addc_u32 s99, s99, 0
	global_load_dwordx4 v[166:169], v155, s[98:99] nt
	global_load_dwordx4 v[170:173], v155, s[98:99] offset:1024 nt
	global_load_dwordx4 v[174:177], v155, s[98:99] offset:2048 nt
	global_load_dwordx4 v[178:181], v155, s[98:99] offset:3072 nt
	global_load_dwordx4 v[182:185], v156, s[98:99] nt
	global_load_dwordx4 v[186:189], v156, s[98:99] offset:1024 nt
	global_load_dwordx4 v[190:193], v156, s[98:99] offset:2048 nt
	global_load_dwordx4 v[194:197], v156, s[98:99] offset:3072 nt
	global_load_dwordx4 v[198:201], v155, s[100:101]
	global_load_dwordx4 v[202:205], v155, s[100:101] offset:1024
	global_load_dwordx4 v[206:209], v155, s[100:101] offset:2048
	global_load_dwordx4 v[210:213], v155, s[100:101] offset:3072
	global_load_dwordx4 v[214:217], v156, s[100:101]
	global_load_dwordx4 v[218:221], v156, s[100:101] offset:1024
	global_load_dwordx4 v[222:225], v156, s[100:101] offset:2048
	global_load_dwordx4 v[228:231], v156, s[100:101] offset:3072
	s_add_i32 s93, s24, 0x2000
	s_lshl_b32 s93, s93, 12
	s_add_u32 s70, s36, s93
	s_addc_u32 s71, s37, 0
	s_waitcnt vmcnt(8)
	v_mul_f32_e32 v159, v166, v166
	v_fmac_f32_e32 v159, v167, v167
	v_fmac_f32_e32 v159, v168, v168
	v_fmac_f32_e32 v159, v169, v169
	v_fmac_f32_e32 v159, v170, v170
	v_fmac_f32_e32 v159, v171, v171
	v_fmac_f32_e32 v159, v172, v172
	v_fmac_f32_e32 v159, v173, v173
	v_fmac_f32_e32 v159, v174, v174
	v_fmac_f32_e32 v159, v175, v175
	v_fmac_f32_e32 v159, v176, v176
	v_fmac_f32_e32 v159, v177, v177
	v_fmac_f32_e32 v159, v178, v178
	v_fmac_f32_e32 v159, v179, v179
	v_fmac_f32_e32 v159, v180, v180
	v_fmac_f32_e32 v159, v181, v181
	v_fmac_f32_e32 v159, v182, v182
	v_fmac_f32_e32 v159, v183, v183
	v_fmac_f32_e32 v159, v184, v184
	v_fmac_f32_e32 v159, v185, v185
	v_fmac_f32_e32 v159, v186, v186
	v_fmac_f32_e32 v159, v187, v187
	v_fmac_f32_e32 v159, v188, v188
	v_fmac_f32_e32 v159, v189, v189
	v_fmac_f32_e32 v159, v190, v190
	v_fmac_f32_e32 v159, v191, v191
	v_fmac_f32_e32 v159, v192, v192
	v_fmac_f32_e32 v159, v193, v193
	v_fmac_f32_e32 v159, v194, v194
	v_fmac_f32_e32 v159, v195, v195
	v_fmac_f32_e32 v159, v196, v196
	v_fmac_f32_e32 v159, v197, v197
	v_xor_b32_e32 v160, 4, v158
	ds_bpermute_b32 v161, v160, v159
	s_waitcnt lgkmcnt(0)
	v_add_f32_e32 v159, v159, v161
	v_xor_b32_e32 v160, 8, v158
	ds_bpermute_b32 v161, v160, v159
	s_waitcnt lgkmcnt(0)
	v_add_f32_e32 v159, v159, v161
	v_xor_b32_e32 v160, 16, v158
	ds_bpermute_b32 v161, v160, v159
	s_waitcnt lgkmcnt(0)
	v_add_f32_e32 v159, v159, v161
	v_xor_b32_e32 v160, 32, v158
	ds_bpermute_b32 v161, v160, v159
	s_waitcnt lgkmcnt(0)
	v_add_f32_e32 v159, v159, v161
	v_xor_b32_e32 v160, 64, v158
	ds_bpermute_b32 v161, v160, v159
	s_waitcnt lgkmcnt(0)
	v_add_f32_e32 v159, v159, v161
	v_xor_b32_e32 v160, 128, v158
	ds_bpermute_b32 v161, v160, v159
	s_waitcnt lgkmcnt(0)
	v_add_f32_e32 v159, v159, v161
	v_mov_b32_e32 v162, 0x3a000000
	v_mov_b32_e32 v163, 0x358637bd
	v_fma_f32 v159, v159, v162, v163
	v_rsq_f32_e32 v159, v159
	s_waitcnt vmcnt(0)
	v_mul_f32_e32 v166, v166, v159
	v_mul_f32_e32 v166, v166, v198
	v_mul_f32_e32 v167, v167, v159
	v_mul_f32_e32 v167, v167, v199
	v_mul_f32_e32 v168, v168, v159
	v_mul_f32_e32 v168, v168, v200
	v_mul_f32_e32 v169, v169, v159
	v_mul_f32_e32 v169, v169, v201
	v_cvt_pk_bf16_f32 v166, v166, v167
	v_cvt_pk_bf16_f32 v167, v168, v169
	global_store_dwordx2 v157, v[166:167], s[70:71]
	v_mul_f32_e32 v170, v170, v159
	v_mul_f32_e32 v170, v170, v202
	v_mul_f32_e32 v171, v171, v159
	v_mul_f32_e32 v171, v171, v203
	v_mul_f32_e32 v172, v172, v159
	v_mul_f32_e32 v172, v172, v204
	v_mul_f32_e32 v173, v173, v159
	v_mul_f32_e32 v173, v173, v205
	v_cvt_pk_bf16_f32 v170, v170, v171
	v_cvt_pk_bf16_f32 v171, v172, v173
	global_store_dwordx2 v157, v[170:171], s[70:71] offset:512
	v_mul_f32_e32 v174, v174, v159
	v_mul_f32_e32 v174, v174, v206
	v_mul_f32_e32 v175, v175, v159
	v_mul_f32_e32 v175, v175, v207
	v_mul_f32_e32 v176, v176, v159
	v_mul_f32_e32 v176, v176, v208
	v_mul_f32_e32 v177, v177, v159
	v_mul_f32_e32 v177, v177, v209
	v_cvt_pk_bf16_f32 v174, v174, v175
	v_cvt_pk_bf16_f32 v175, v176, v177
	global_store_dwordx2 v157, v[174:175], s[70:71] offset:1024
	v_mul_f32_e32 v178, v178, v159
	v_mul_f32_e32 v178, v178, v210
	v_mul_f32_e32 v179, v179, v159
	v_mul_f32_e32 v179, v179, v211
	v_mul_f32_e32 v180, v180, v159
	v_mul_f32_e32 v180, v180, v212
	v_mul_f32_e32 v181, v181, v159
	v_mul_f32_e32 v181, v181, v213
	v_cvt_pk_bf16_f32 v178, v178, v179
	v_cvt_pk_bf16_f32 v179, v180, v181
	global_store_dwordx2 v157, v[178:179], s[70:71] offset:1536
	v_mul_f32_e32 v182, v182, v159
	v_mul_f32_e32 v182, v182, v214
	v_mul_f32_e32 v183, v183, v159
	v_mul_f32_e32 v183, v183, v215
	v_mul_f32_e32 v184, v184, v159
	v_mul_f32_e32 v184, v184, v216
	v_mul_f32_e32 v185, v185, v159
	v_mul_f32_e32 v185, v185, v217
	v_cvt_pk_bf16_f32 v182, v182, v183
	v_cvt_pk_bf16_f32 v183, v184, v185
	global_store_dwordx2 v157, v[182:183], s[70:71] offset:2048
	v_mul_f32_e32 v186, v186, v159
	v_mul_f32_e32 v186, v186, v218
	v_mul_f32_e32 v187, v187, v159
	v_mul_f32_e32 v187, v187, v219
	v_mul_f32_e32 v188, v188, v159
	v_mul_f32_e32 v188, v188, v220
	v_mul_f32_e32 v189, v189, v159
	v_mul_f32_e32 v189, v189, v221
	v_cvt_pk_bf16_f32 v186, v186, v187
	v_cvt_pk_bf16_f32 v187, v188, v189
	global_store_dwordx2 v157, v[186:187], s[70:71] offset:2560
	v_mul_f32_e32 v190, v190, v159
	v_mul_f32_e32 v190, v190, v222
	v_mul_f32_e32 v191, v191, v159
	v_mul_f32_e32 v191, v191, v223
	v_mul_f32_e32 v192, v192, v159
	v_mul_f32_e32 v192, v192, v224
	v_mul_f32_e32 v193, v193, v159
	v_mul_f32_e32 v193, v193, v225
	v_cvt_pk_bf16_f32 v190, v190, v191
	v_cvt_pk_bf16_f32 v191, v192, v193
	global_store_dwordx2 v157, v[190:191], s[70:71] offset:3072
	v_mul_f32_e32 v194, v194, v159
	v_mul_f32_e32 v194, v194, v228
	v_mul_f32_e32 v195, v195, v159
	v_mul_f32_e32 v195, v195, v229
	v_mul_f32_e32 v196, v196, v159
	v_mul_f32_e32 v196, v196, v230
	v_mul_f32_e32 v197, v197, v159
	v_mul_f32_e32 v197, v197, v231
	v_cvt_pk_bf16_f32 v194, v194, v195
	v_cvt_pk_bf16_f32 v195, v196, v197
	global_store_dwordx2 v157, v[194:195], s[70:71] offset:3584
	s_branch .LBB0_44
